# single edit edit_attn_lagdma
# speedup vs baseline: 1.0036x; 1.0036x over previous
.LBB0_717:
	s_add_i32 s53, s55, 1
	s_mov_b32 s52, s47
	s_mov_b32 s47, s54
	s_and_b64 vcc, exec, s[4:5]
	s_cbranch_vccnz .Lattn_lag
	s_cmp_ge_u32 s53, s43
	s_cbranch_scc1 .LBB0_724
	s_bitcmp1_b32 s53, 0
	s_cselect_b32 s54, 0x6000, 0
	s_add_i32 s54, s54, 0
	v_lshl_add_u64 v[130:131], v[180:181], 0, v[166:167]
	s_add_i32 m0, s54, s23
	s_nop 0
	global_load_lds_dwordx4 v[130:131], off
	v_lshl_add_u64 v[130:131], v[178:179], 0, v[166:167]
	s_add_i32 m0, s54, s24
	s_nop 0
	global_load_lds_dwordx4 v[130:131], off
	s_add_i32 m0, s54, s25
	s_lshl_b32 s54, s44, 14
	s_add_i32 s54, s54, 0
	v_lshl_add_u64 v[130:131], v[176:177], 0, v[166:167]
	s_add_i32 s56, s54, s23
	global_load_lds_dwordx4 v[130:131], off
	v_lshl_add_u64 v[130:131], v[182:183], 0, v[166:167]
	s_add_i32 m0, s56, 0xc000
	s_add_i32 s54, s54, s24
	global_load_lds_dwordx4 v[130:131], off
	v_lshl_add_u64 v[130:131], v[184:185], 0, v[166:167]
	s_add_i32 m0, s54, 0xc000
	s_nop 0
	global_load_lds_dwordx4 v[130:131], off
	s_andn2_b64 vcc, exec, s[4:5]
	s_cbranch_vccz .LBB0_725

.Lattn_lag:
	v_lshl_add_u32 v0, s52, 14, v234
	ds_read_b128 v[130:133], v0 offset:49152
	ds_read_b128 v[134:137], v0 offset:50176
	ds_read_b128 v[138:141], v0 offset:51200
	ds_read_b128 v[142:145], v0 offset:52224
	s_waitcnt lgkmcnt(0)
	v_mfma_f32_16x16x32_bf16 v[110:113], v[130:133], v[114:117], v[110:113]
	v_mfma_f32_16x16x32_bf16 v[30:33], v[130:133], v[122:125], v[30:33]
	v_mfma_f32_16x16x32_bf16 v[110:113], v[134:137], v[118:121], v[110:113]
	v_mfma_f32_16x16x32_bf16 v[30:33], v[134:137], v[126:129], v[30:33]
	ds_read_b128 v[130:133], v0 offset:53248
	ds_read_b128 v[134:137], v0 offset:54272
	v_mfma_f32_16x16x32_bf16 v[106:109], v[138:141], v[114:117], v[106:109]
	v_mfma_f32_16x16x32_bf16 v[26:29], v[138:141], v[122:125], v[26:29]
	v_mfma_f32_16x16x32_bf16 v[106:109], v[142:145], v[118:121], v[106:109]
	v_mfma_f32_16x16x32_bf16 v[26:29], v[142:145], v[126:129], v[26:29]
	ds_read_b128 v[138:141], v0 offset:55296
	ds_read_b128 v[142:145], v0 offset:56320
	s_waitcnt lgkmcnt(0)
	v_mfma_f32_16x16x32_bf16 v[102:105], v[130:133], v[114:117], v[102:105]
	v_mfma_f32_16x16x32_bf16 v[22:25], v[130:133], v[122:125], v[22:25]
	v_mfma_f32_16x16x32_bf16 v[102:105], v[134:137], v[118:121], v[102:105]
	v_mfma_f32_16x16x32_bf16 v[22:25], v[134:137], v[126:129], v[22:25]
	ds_read_b128 v[130:133], v0 offset:57344
	ds_read_b128 v[134:137], v0 offset:58368
	v_mfma_f32_16x16x32_bf16 v[98:101], v[138:141], v[114:117], v[98:101]
	v_mfma_f32_16x16x32_bf16 v[18:21], v[138:141], v[122:125], v[18:21]
	v_mfma_f32_16x16x32_bf16 v[98:101], v[142:145], v[118:121], v[98:101]
	v_mfma_f32_16x16x32_bf16 v[18:21], v[142:145], v[126:129], v[18:21]
	ds_read_b128 v[138:141], v0 offset:59392
	ds_read_b128 v[142:145], v0 offset:60416
	s_waitcnt lgkmcnt(0)
	v_mfma_f32_16x16x32_bf16 v[90:93], v[130:133], v[114:117], v[90:93]
	v_mfma_f32_16x16x32_bf16 v[14:17], v[130:133], v[122:125], v[14:17]
	v_mfma_f32_16x16x32_bf16 v[90:93], v[134:137], v[118:121], v[90:93]
	v_mfma_f32_16x16x32_bf16 v[14:17], v[134:137], v[126:129], v[14:17]
	ds_read_b128 v[130:133], v0 offset:61440
	ds_read_b128 v[134:137], v0 offset:62464
	v_mfma_f32_16x16x32_bf16 v[70:73], v[138:141], v[114:117], v[70:73]
	v_mfma_f32_16x16x32_bf16 v[10:13], v[138:141], v[122:125], v[10:13]
	v_mfma_f32_16x16x32_bf16 v[70:73], v[142:145], v[118:121], v[70:73]
	v_mfma_f32_16x16x32_bf16 v[10:13], v[142:145], v[126:129], v[10:13]
	ds_read_b128 v[138:141], v0 offset:63488
	ds_read_b128 v[142:145], v0 offset:64512
	s_waitcnt lgkmcnt(0)
	v_mfma_f32_16x16x32_bf16 v[38:41], v[130:133], v[114:117], v[38:41]
	v_mfma_f32_16x16x32_bf16 v[6:9], v[130:133], v[122:125], v[6:9]
	v_mfma_f32_16x16x32_bf16 v[38:41], v[134:137], v[118:121], v[38:41]
	v_mfma_f32_16x16x32_bf16 v[6:9], v[134:137], v[126:129], v[6:9]
	v_mfma_f32_16x16x32_bf16 v[34:37], v[138:141], v[114:117], v[34:37]
	v_mfma_f32_16x16x32_bf16 v[2:5], v[138:141], v[122:125], v[2:5]
	v_mfma_f32_16x16x32_bf16 v[34:37], v[142:145], v[118:121], v[34:37]
	v_mfma_f32_16x16x32_bf16 v[2:5], v[142:145], v[126:129], v[2:5]
	s_cmp_ge_u32 s53, s43
	s_cbranch_scc1 .Lattn_lag_nodma
	s_bitcmp1_b32 s53, 0
	s_cselect_b32 s54, 0x6000, 0
	s_add_i32 s54, s54, 0
	v_lshl_add_u64 v[130:131], v[180:181], 0, v[166:167]
	s_add_i32 m0, s54, s23
	s_nop 0
	global_load_lds_dwordx4 v[130:131], off
	v_lshl_add_u64 v[130:131], v[178:179], 0, v[166:167]
	s_add_i32 m0, s54, s24
	s_nop 0
	global_load_lds_dwordx4 v[130:131], off
	s_add_i32 m0, s54, s25
	s_lshl_b32 s54, s44, 14
	s_add_i32 s54, s54, 0
	v_lshl_add_u64 v[130:131], v[176:177], 0, v[166:167]
	s_add_i32 s56, s54, s23
	global_load_lds_dwordx4 v[130:131], off
	v_lshl_add_u64 v[130:131], v[182:183], 0, v[166:167]
	s_add_i32 m0, s56, 0xc000
	s_add_i32 s54, s54, s24
	global_load_lds_dwordx4 v[130:131], off
	v_lshl_add_u64 v[130:131], v[184:185], 0, v[166:167]
	s_add_i32 m0, s54, 0xc000
	s_nop 0
	global_load_lds_dwordx4 v[130:131], off
.Lattn_lag_nodma:
	s_lshl_b32 s4, s47, 14
	s_add_i32 s54, s4, 0
	s_cmp_gt_i32 s42, s45
	s_cbranch_scc0 .LBB0_720
	s_branch .LBB0_726
